# same as v38 plus one s_nop before the last in-block DPP fmac of the P5 forward substitution (conservative DPP wait states)
# speedup vs baseline: 1.0011x; 1.0011x over previous
; __device__ __forceinline__ void prep_unit(const int PREP_STEPS, LAS unsigned char* lds, int uidx, bf16* Qg, bf16* Kg, bf16* Vg, bf16* KT, bf16* QK, const bf16* HALO, const float* wconv, const float* BETA, const float* GG, float* GC) {
;     ...
; #pragma unroll
;             for (int q = 0; q < 15; ++q) {
;                 const float xu = au[q], xw = aw[q];
;                 const int av = __builtin_bit_cast(int, Af[(16 * I + q) * 68 + 16 * I + l16]);
;                 Rows16<0>::run(av, xu, xw, au, aw, q);
;             }
.Lfs_q:
	s_mul_i32 s0, s1, 0x1140
	v_add_u32_e32 v19, s0, v145
	ds_read_b32 v20, v19
	ds_read_b32 v21, v19 offset:272
	ds_read_b32 v22, v19 offset:544
	ds_read_b32 v23, v19 offset:816
	ds_read_b32 v24, v19 offset:1088
	ds_read_b32 v25, v19 offset:1360
	ds_read_b32 v26, v19 offset:1632
	ds_read_b32 v27, v19 offset:1904
	ds_read_b32 v28, v19 offset:2176
	ds_read_b32 v29, v19 offset:2448
	ds_read_b32 v30, v19 offset:2720
	ds_read_b32 v31, v19 offset:2992
	ds_read_b32 v32, v19 offset:3264
	ds_read_b32 v33, v19 offset:3536
	ds_read_b32 v34, v19 offset:3808
	s_waitcnt lgkmcnt(14)
	v_fmac_f32_dpp v4, v20, v0 row_newbcast:1 row_mask:0xf bank_mask:0xf bound_ctrl:1
	v_fmac_f32_dpp v8, v20, v0 row_newbcast:2 row_mask:0xf bank_mask:0xf bound_ctrl:1
	v_fmac_f32_dpp v12, v20, v0 row_newbcast:3 row_mask:0xf bank_mask:0xf bound_ctrl:1
	v_fmac_f32_dpp v1, v20, v0 row_newbcast:4 row_mask:0xf bank_mask:0xf bound_ctrl:1
	v_fmac_f32_dpp v5, v20, v0 row_newbcast:5 row_mask:0xf bank_mask:0xf bound_ctrl:1
	v_fmac_f32_dpp v9, v20, v0 row_newbcast:6 row_mask:0xf bank_mask:0xf bound_ctrl:1
	v_fmac_f32_dpp v13, v20, v0 row_newbcast:7 row_mask:0xf bank_mask:0xf bound_ctrl:1
	v_fmac_f32_dpp v2, v20, v0 row_newbcast:8 row_mask:0xf bank_mask:0xf bound_ctrl:1
	v_fmac_f32_dpp v6, v20, v0 row_newbcast:9 row_mask:0xf bank_mask:0xf bound_ctrl:1
	v_fmac_f32_dpp v10, v20, v0 row_newbcast:10 row_mask:0xf bank_mask:0xf bound_ctrl:1
	v_fmac_f32_dpp v14, v20, v0 row_newbcast:11 row_mask:0xf bank_mask:0xf bound_ctrl:1
	v_fmac_f32_dpp v3, v20, v0 row_newbcast:12 row_mask:0xf bank_mask:0xf bound_ctrl:1
	v_fmac_f32_dpp v7, v20, v0 row_newbcast:13 row_mask:0xf bank_mask:0xf bound_ctrl:1
	v_fmac_f32_dpp v11, v20, v0 row_newbcast:14 row_mask:0xf bank_mask:0xf bound_ctrl:1
	v_fmac_f32_dpp v15, v20, v0 row_newbcast:15 row_mask:0xf bank_mask:0xf bound_ctrl:1
	s_waitcnt lgkmcnt(13)
	v_fmac_f32_dpp v8, v21, v4 row_newbcast:2 row_mask:0xf bank_mask:0xf bound_ctrl:1
	v_fmac_f32_dpp v12, v21, v4 row_newbcast:3 row_mask:0xf bank_mask:0xf bound_ctrl:1
	v_fmac_f32_dpp v1, v21, v4 row_newbcast:4 row_mask:0xf bank_mask:0xf bound_ctrl:1
	v_fmac_f32_dpp v5, v21, v4 row_newbcast:5 row_mask:0xf bank_mask:0xf bound_ctrl:1
	v_fmac_f32_dpp v9, v21, v4 row_newbcast:6 row_mask:0xf bank_mask:0xf bound_ctrl:1
	v_fmac_f32_dpp v13, v21, v4 row_newbcast:7 row_mask:0xf bank_mask:0xf bound_ctrl:1
	v_fmac_f32_dpp v2, v21, v4 row_newbcast:8 row_mask:0xf bank_mask:0xf bound_ctrl:1
	v_fmac_f32_dpp v6, v21, v4 row_newbcast:9 row_mask:0xf bank_mask:0xf bound_ctrl:1
	v_fmac_f32_dpp v10, v21, v4 row_newbcast:10 row_mask:0xf bank_mask:0xf bound_ctrl:1
	v_fmac_f32_dpp v14, v21, v4 row_newbcast:11 row_mask:0xf bank_mask:0xf bound_ctrl:1
	v_fmac_f32_dpp v3, v21, v4 row_newbcast:12 row_mask:0xf bank_mask:0xf bound_ctrl:1
	v_fmac_f32_dpp v7, v21, v4 row_newbcast:13 row_mask:0xf bank_mask:0xf bound_ctrl:1
	v_fmac_f32_dpp v11, v21, v4 row_newbcast:14 row_mask:0xf bank_mask:0xf bound_ctrl:1
	v_fmac_f32_dpp v15, v21, v4 row_newbcast:15 row_mask:0xf bank_mask:0xf bound_ctrl:1
	s_waitcnt lgkmcnt(12)
	v_fmac_f32_dpp v12, v22, v8 row_newbcast:3 row_mask:0xf bank_mask:0xf bound_ctrl:1
	v_fmac_f32_dpp v1, v22, v8 row_newbcast:4 row_mask:0xf bank_mask:0xf bound_ctrl:1
	v_fmac_f32_dpp v5, v22, v8 row_newbcast:5 row_mask:0xf bank_mask:0xf bound_ctrl:1
	v_fmac_f32_dpp v9, v22, v8 row_newbcast:6 row_mask:0xf bank_mask:0xf bound_ctrl:1
	v_fmac_f32_dpp v13, v22, v8 row_newbcast:7 row_mask:0xf bank_mask:0xf bound_ctrl:1
	v_fmac_f32_dpp v2, v22, v8 row_newbcast:8 row_mask:0xf bank_mask:0xf bound_ctrl:1
	v_fmac_f32_dpp v6, v22, v8 row_newbcast:9 row_mask:0xf bank_mask:0xf bound_ctrl:1
	v_fmac_f32_dpp v10, v22, v8 row_newbcast:10 row_mask:0xf bank_mask:0xf bound_ctrl:1
	v_fmac_f32_dpp v14, v22, v8 row_newbcast:11 row_mask:0xf bank_mask:0xf bound_ctrl:1
	v_fmac_f32_dpp v3, v22, v8 row_newbcast:12 row_mask:0xf bank_mask:0xf bound_ctrl:1
	v_fmac_f32_dpp v7, v22, v8 row_newbcast:13 row_mask:0xf bank_mask:0xf bound_ctrl:1
	v_fmac_f32_dpp v11, v22, v8 row_newbcast:14 row_mask:0xf bank_mask:0xf bound_ctrl:1
	v_fmac_f32_dpp v15, v22, v8 row_newbcast:15 row_mask:0xf bank_mask:0xf bound_ctrl:1
	s_waitcnt lgkmcnt(11)
	v_fmac_f32_dpp v1, v23, v12 row_newbcast:4 row_mask:0xf bank_mask:0xf bound_ctrl:1
	v_fmac_f32_dpp v5, v23, v12 row_newbcast:5 row_mask:0xf bank_mask:0xf bound_ctrl:1
	v_fmac_f32_dpp v9, v23, v12 row_newbcast:6 row_mask:0xf bank_mask:0xf bound_ctrl:1
	v_fmac_f32_dpp v13, v23, v12 row_newbcast:7 row_mask:0xf bank_mask:0xf bound_ctrl:1
	v_fmac_f32_dpp v2, v23, v12 row_newbcast:8 row_mask:0xf bank_mask:0xf bound_ctrl:1
	v_fmac_f32_dpp v6, v23, v12 row_newbcast:9 row_mask:0xf bank_mask:0xf bound_ctrl:1
	v_fmac_f32_dpp v10, v23, v12 row_newbcast:10 row_mask:0xf bank_mask:0xf bound_ctrl:1
	v_fmac_f32_dpp v14, v23, v12 row_newbcast:11 row_mask:0xf bank_mask:0xf bound_ctrl:1
	v_fmac_f32_dpp v3, v23, v12 row_newbcast:12 row_mask:0xf bank_mask:0xf bound_ctrl:1
	v_fmac_f32_dpp v7, v23, v12 row_newbcast:13 row_mask:0xf bank_mask:0xf bound_ctrl:1
	v_fmac_f32_dpp v11, v23, v12 row_newbcast:14 row_mask:0xf bank_mask:0xf bound_ctrl:1
	v_fmac_f32_dpp v15, v23, v12 row_newbcast:15 row_mask:0xf bank_mask:0xf bound_ctrl:1
	s_waitcnt lgkmcnt(10)
; __device__ __forceinline__ unsigned short f2bf(float f) { return (unsigned short)(cvt_pk_bf16(f, 0.f) & 0xffffu); }
; __device__ __forceinline__ void prep_unit(const int PREP_STEPS, LAS unsigned char* lds, int uidx, bf16* Qg, bf16* Kg, bf16* Vg, bf16* KT, bf16* QK, const bf16* HALO, const float* wconv, const float* BETA, const float* GG, float* GC) {
;     ...
;             for (int q = 0; q < 15; ++q) {
;                 const float xu = au[q], xw = aw[q];
;                 const int av = __builtin_bit_cast(int, Af[(16 * I + q) * 68 + 16 * I + l16]);
;                 Rows16<0>::run(av, xu, xw, au, aw, q);
;             }
; #pragma unroll
;             for (int r = 0; r < 16; ++r) { const unsigned short ub = f2bf(au[r]), wb = f2bf(aw[r]); Vs[(16 * I + r) * 136 + c] = ub; Ks[(16 * I + r) * 136 + c] = wb;
;                 dstu[(size_t)(16 * I + r) * D] = ub; dstw[(size_t)(16 * I + r) * D] = wb; }
	v_fmac_f32_dpp v5, v24, v1 row_newbcast:5 row_mask:0xf bank_mask:0xf bound_ctrl:1
	v_fmac_f32_dpp v9, v24, v1 row_newbcast:6 row_mask:0xf bank_mask:0xf bound_ctrl:1
	v_fmac_f32_dpp v13, v24, v1 row_newbcast:7 row_mask:0xf bank_mask:0xf bound_ctrl:1
	v_fmac_f32_dpp v2, v24, v1 row_newbcast:8 row_mask:0xf bank_mask:0xf bound_ctrl:1
	v_fmac_f32_dpp v6, v24, v1 row_newbcast:9 row_mask:0xf bank_mask:0xf bound_ctrl:1
	v_fmac_f32_dpp v10, v24, v1 row_newbcast:10 row_mask:0xf bank_mask:0xf bound_ctrl:1
	v_fmac_f32_dpp v14, v24, v1 row_newbcast:11 row_mask:0xf bank_mask:0xf bound_ctrl:1
	v_fmac_f32_dpp v3, v24, v1 row_newbcast:12 row_mask:0xf bank_mask:0xf bound_ctrl:1
	v_fmac_f32_dpp v7, v24, v1 row_newbcast:13 row_mask:0xf bank_mask:0xf bound_ctrl:1
	v_fmac_f32_dpp v11, v24, v1 row_newbcast:14 row_mask:0xf bank_mask:0xf bound_ctrl:1
	v_fmac_f32_dpp v15, v24, v1 row_newbcast:15 row_mask:0xf bank_mask:0xf bound_ctrl:1
	s_waitcnt lgkmcnt(9)
	v_fmac_f32_dpp v9, v25, v5 row_newbcast:6 row_mask:0xf bank_mask:0xf bound_ctrl:1
	v_fmac_f32_dpp v13, v25, v5 row_newbcast:7 row_mask:0xf bank_mask:0xf bound_ctrl:1
	v_fmac_f32_dpp v2, v25, v5 row_newbcast:8 row_mask:0xf bank_mask:0xf bound_ctrl:1
	v_fmac_f32_dpp v6, v25, v5 row_newbcast:9 row_mask:0xf bank_mask:0xf bound_ctrl:1
	v_fmac_f32_dpp v10, v25, v5 row_newbcast:10 row_mask:0xf bank_mask:0xf bound_ctrl:1
	v_fmac_f32_dpp v14, v25, v5 row_newbcast:11 row_mask:0xf bank_mask:0xf bound_ctrl:1
	v_fmac_f32_dpp v3, v25, v5 row_newbcast:12 row_mask:0xf bank_mask:0xf bound_ctrl:1
	v_fmac_f32_dpp v7, v25, v5 row_newbcast:13 row_mask:0xf bank_mask:0xf bound_ctrl:1
	v_fmac_f32_dpp v11, v25, v5 row_newbcast:14 row_mask:0xf bank_mask:0xf bound_ctrl:1
	v_fmac_f32_dpp v15, v25, v5 row_newbcast:15 row_mask:0xf bank_mask:0xf bound_ctrl:1
	s_waitcnt lgkmcnt(8)
	v_fmac_f32_dpp v13, v26, v9 row_newbcast:7 row_mask:0xf bank_mask:0xf bound_ctrl:1
	v_fmac_f32_dpp v2, v26, v9 row_newbcast:8 row_mask:0xf bank_mask:0xf bound_ctrl:1
	v_fmac_f32_dpp v6, v26, v9 row_newbcast:9 row_mask:0xf bank_mask:0xf bound_ctrl:1
	v_fmac_f32_dpp v10, v26, v9 row_newbcast:10 row_mask:0xf bank_mask:0xf bound_ctrl:1
	v_fmac_f32_dpp v14, v26, v9 row_newbcast:11 row_mask:0xf bank_mask:0xf bound_ctrl:1
	v_fmac_f32_dpp v3, v26, v9 row_newbcast:12 row_mask:0xf bank_mask:0xf bound_ctrl:1
	v_fmac_f32_dpp v7, v26, v9 row_newbcast:13 row_mask:0xf bank_mask:0xf bound_ctrl:1
	v_fmac_f32_dpp v11, v26, v9 row_newbcast:14 row_mask:0xf bank_mask:0xf bound_ctrl:1
	v_fmac_f32_dpp v15, v26, v9 row_newbcast:15 row_mask:0xf bank_mask:0xf bound_ctrl:1
	s_waitcnt lgkmcnt(7)
	v_fmac_f32_dpp v2, v27, v13 row_newbcast:8 row_mask:0xf bank_mask:0xf bound_ctrl:1
	v_fmac_f32_dpp v6, v27, v13 row_newbcast:9 row_mask:0xf bank_mask:0xf bound_ctrl:1
	v_fmac_f32_dpp v10, v27, v13 row_newbcast:10 row_mask:0xf bank_mask:0xf bound_ctrl:1
	v_fmac_f32_dpp v14, v27, v13 row_newbcast:11 row_mask:0xf bank_mask:0xf bound_ctrl:1
	v_fmac_f32_dpp v3, v27, v13 row_newbcast:12 row_mask:0xf bank_mask:0xf bound_ctrl:1
	v_fmac_f32_dpp v7, v27, v13 row_newbcast:13 row_mask:0xf bank_mask:0xf bound_ctrl:1
	v_fmac_f32_dpp v11, v27, v13 row_newbcast:14 row_mask:0xf bank_mask:0xf bound_ctrl:1
	v_fmac_f32_dpp v15, v27, v13 row_newbcast:15 row_mask:0xf bank_mask:0xf bound_ctrl:1
	s_waitcnt lgkmcnt(6)
	v_fmac_f32_dpp v6, v28, v2 row_newbcast:9 row_mask:0xf bank_mask:0xf bound_ctrl:1
	v_fmac_f32_dpp v10, v28, v2 row_newbcast:10 row_mask:0xf bank_mask:0xf bound_ctrl:1
	v_fmac_f32_dpp v14, v28, v2 row_newbcast:11 row_mask:0xf bank_mask:0xf bound_ctrl:1
	v_fmac_f32_dpp v3, v28, v2 row_newbcast:12 row_mask:0xf bank_mask:0xf bound_ctrl:1
	v_fmac_f32_dpp v7, v28, v2 row_newbcast:13 row_mask:0xf bank_mask:0xf bound_ctrl:1
	v_fmac_f32_dpp v11, v28, v2 row_newbcast:14 row_mask:0xf bank_mask:0xf bound_ctrl:1
	v_fmac_f32_dpp v15, v28, v2 row_newbcast:15 row_mask:0xf bank_mask:0xf bound_ctrl:1
	s_waitcnt lgkmcnt(5)
	v_fmac_f32_dpp v10, v29, v6 row_newbcast:10 row_mask:0xf bank_mask:0xf bound_ctrl:1
	v_fmac_f32_dpp v14, v29, v6 row_newbcast:11 row_mask:0xf bank_mask:0xf bound_ctrl:1
	v_fmac_f32_dpp v3, v29, v6 row_newbcast:12 row_mask:0xf bank_mask:0xf bound_ctrl:1
	v_fmac_f32_dpp v7, v29, v6 row_newbcast:13 row_mask:0xf bank_mask:0xf bound_ctrl:1
	v_fmac_f32_dpp v11, v29, v6 row_newbcast:14 row_mask:0xf bank_mask:0xf bound_ctrl:1
	v_fmac_f32_dpp v15, v29, v6 row_newbcast:15 row_mask:0xf bank_mask:0xf bound_ctrl:1
	s_waitcnt lgkmcnt(4)
	v_fmac_f32_dpp v14, v30, v10 row_newbcast:11 row_mask:0xf bank_mask:0xf bound_ctrl:1
	v_fmac_f32_dpp v3, v30, v10 row_newbcast:12 row_mask:0xf bank_mask:0xf bound_ctrl:1
	v_fmac_f32_dpp v7, v30, v10 row_newbcast:13 row_mask:0xf bank_mask:0xf bound_ctrl:1
	v_fmac_f32_dpp v11, v30, v10 row_newbcast:14 row_mask:0xf bank_mask:0xf bound_ctrl:1
	v_fmac_f32_dpp v15, v30, v10 row_newbcast:15 row_mask:0xf bank_mask:0xf bound_ctrl:1
	s_waitcnt lgkmcnt(3)
	v_fmac_f32_dpp v3, v31, v14 row_newbcast:12 row_mask:0xf bank_mask:0xf bound_ctrl:1
	v_fmac_f32_dpp v7, v31, v14 row_newbcast:13 row_mask:0xf bank_mask:0xf bound_ctrl:1
	v_fmac_f32_dpp v11, v31, v14 row_newbcast:14 row_mask:0xf bank_mask:0xf bound_ctrl:1
	v_fmac_f32_dpp v15, v31, v14 row_newbcast:15 row_mask:0xf bank_mask:0xf bound_ctrl:1
	s_waitcnt lgkmcnt(2)
	v_fmac_f32_dpp v7, v32, v3 row_newbcast:13 row_mask:0xf bank_mask:0xf bound_ctrl:1
	v_fmac_f32_dpp v11, v32, v3 row_newbcast:14 row_mask:0xf bank_mask:0xf bound_ctrl:1
	v_fmac_f32_dpp v15, v32, v3 row_newbcast:15 row_mask:0xf bank_mask:0xf bound_ctrl:1
	s_waitcnt lgkmcnt(1)
	v_fmac_f32_dpp v11, v33, v7 row_newbcast:14 row_mask:0xf bank_mask:0xf bound_ctrl:1
	v_fmac_f32_dpp v15, v33, v7 row_newbcast:15 row_mask:0xf bank_mask:0xf bound_ctrl:1
	s_waitcnt lgkmcnt(0)
	s_nop 1
	v_fmac_f32_dpp v15, v34, v11 row_newbcast:15 row_mask:0xf bank_mask:0xf bound_ctrl:1
	v_cvt_pk_bf16_f32 v20, v0, v0
	v_cvt_pk_bf16_f32 v21, v4, v4
	v_cvt_pk_bf16_f32 v22, v8, v8
	v_cvt_pk_bf16_f32 v23, v12, v12
	v_cvt_pk_bf16_f32 v24, v1, v1
	v_cvt_pk_bf16_f32 v25, v5, v5
	v_cvt_pk_bf16_f32 v26, v9, v9
	v_cvt_pk_bf16_f32 v27, v13, v13
	v_cvt_pk_bf16_f32 v28, v2, v2
	v_cvt_pk_bf16_f32 v29, v6, v6
	v_cvt_pk_bf16_f32 v30, v10, v10
	v_cvt_pk_bf16_f32 v31, v14, v14
	v_cvt_pk_bf16_f32 v32, v3, v3
	v_cvt_pk_bf16_f32 v33, v7, v7
	v_cvt_pk_bf16_f32 v34, v11, v11
	v_cvt_pk_bf16_f32 v35, v15, v15
	ds_write_b16 v17, v20
	ds_write_b16 v17, v21 offset:272
	ds_write_b16 v17, v22 offset:544
	ds_write_b16 v17, v23 offset:816
	ds_write_b16 v17, v24 offset:1088
	ds_write_b16 v17, v25 offset:1360
	ds_write_b16 v17, v26 offset:1632
	ds_write_b16 v17, v27 offset:1904
	ds_write_b16 v17, v28 offset:2176
	ds_write_b16 v17, v29 offset:2448
	ds_write_b16 v17, v30 offset:2720
	ds_write_b16 v17, v31 offset:2992
	ds_write_b16 v17, v32 offset:3264
	ds_write_b16 v17, v33 offset:3536
	ds_write_b16 v17, v34 offset:3808
	ds_write_b16 v17, v35 offset:4080
	v_add_u32_e32 v17, 0x1100, v17
	v_add_u32_e32 v48, 64, v48
	s_add_i32 s1, s1, 1
	s_cmp_lg_u32 s1, 4
	s_cbranch_scc1 .Lfs_I
	s_branch .LBB0_637
